# grid barrier: L1 invalidate (acquire) issued at arrival next to the arrival atomic instead of after the release is observed; its completion overlaps the wait (on full_c minus leader reorder)
# speedup vs baseline: 1.0172x; 1.0172x over previous
; __device__ __forceinline__ unsigned xb_ld(unsigned* p)              { return __hip_atomic_load(p, __ATOMIC_RELAXED, __HIP_MEMORY_SCOPE_AGENT); }
; __device__ __forceinline__ unsigned xb_add(unsigned* p, unsigned v) { return __hip_atomic_fetch_add(p, v, __ATOMIC_RELAXED, __HIP_MEMORY_SCOPE_AGENT); }
; #define XB_SPIN(cond, bar) do { unsigned _sp = 0; while (cond) { __builtin_amdgcn_s_sleep(1); \
;     if ((++_sp & 255u) == 0u) { if (xb_ld(&(bar)[XB_TMO])) break; if (_sp > XB_SPIN_CAP) { atomicAdd(&(bar)[XB_TMO], 1u); break; } } } } while (0)
; __device__ __forceinline__ void xcd_barrier(const XcdBarrier& b) {
;     ...
;     if (threadIdx.x == 0) {
;         unsigned* bar = b.bar;
;         __builtin_amdgcn_s_waitcnt(0);
;         unsigned nloc = b.st[0], nx = b.st[1];
;         if (nloc == 0u) { xcd_barrier_complete(bar, b.x, nloc, nx); b.st[0] = nloc; b.st[1] = nx; }
;         const unsigned old = xb_add(&bar[XB_XSUB(b.x)], 1u);
;         const unsigned gen = old / nloc;
;         if (old + 1u == (gen + 1u) * nloc) {
;             __builtin_amdgcn_fence(__ATOMIC_RELEASE, "agent");
;             asm volatile("s_waitcnt vmcnt(0)" ::: "memory");
;             const unsigned og = xb_add(&bar[XB_TOP], 1u);
;             const unsigned tg = og / nx;
;             if (og + 1u == (tg + 1u) * nx) xb_add(&bar[XB_TOPGEN], 1u);
;             else XB_SPIN(xb_ld(&bar[XB_TOPGEN]) == tg, bar);
;             __builtin_amdgcn_fence(__ATOMIC_ACQUIRE, "agent");
;             xb_add(&bar[XB_XGEN(b.x)], 1u);
;             asm volatile("s_waitcnt vmcnt(0)" ::: "memory");
;         } else {
;             XB_SPIN(xb_ld(&bar[XB_XGEN(b.x)]) == gen, bar);
.LBB0_70:
	s_lshl_b32 s3, s33, 8
	s_add_u32 s6, s38, s3
	s_addc_u32 s7, s39, 0
	v_mov_b32_e32 v2, 0x1000
	v_mov_b32_e32 v4, 1
	buffer_inv sc1
	global_atomic_add v4, v2, v4, s[6:7] offset:1024 sc0
	v_cvt_f32_u32_e32 v2, v3
	v_sub_u32_e32 v5, 0, v3
	v_rcp_iflag_f32_e32 v2, v2
	s_nop 0
	v_mul_f32_e32 v2, 0x4f7ffffe, v2
	v_cvt_u32_f32_e32 v2, v2
	v_mul_lo_u32 v5, v5, v2
	v_mul_hi_u32 v5, v2, v5
	v_add_u32_e32 v2, v2, v5
	s_waitcnt vmcnt(0)
	v_mul_hi_u32 v2, v4, v2
	v_mul_lo_u32 v5, v2, v3
	v_sub_u32_e32 v5, v4, v5
	v_add_u32_e32 v6, 1, v2
	v_cmp_ge_u32_e32 vcc, v5, v3
	v_add_u32_e32 v4, 1, v4
	s_nop 0
	v_cndmask_b32_e32 v2, v2, v6, vcc
	v_sub_u32_e32 v6, v5, v3
	v_cndmask_b32_e32 v5, v5, v6, vcc
	v_add_u32_e32 v6, 1, v2
	v_cmp_ge_u32_e32 vcc, v5, v3
	s_nop 1
	v_cndmask_b32_e32 v2, v2, v6, vcc
	v_mul_lo_u32 v5, v3, v2
	v_add_u32_e32 v3, v5, v3
	v_cmp_ne_u32_e32 vcc, v4, v3
	s_and_saveexec_b64 s[14:15], vcc
	s_xor_b64 s[14:15], exec, s[14:15]
	s_cbranch_execz .LBB0_84
	s_waitcnt lgkmcnt(0)
	v_mov_b32_e32 v1, 0x2000
	global_load_dword v1, v1, s[6:7] offset:1024 sc1
	s_add_u32 s20, s6, 0x2400
	s_addc_u32 s21, s7, 0
	s_waitcnt vmcnt(0)
	v_cmp_eq_u32_e32 vcc, v1, v2
	s_and_saveexec_b64 s[16:17], vcc
	s_cbranch_execz .LBB0_83
	s_add_u32 s18, s54, 0x4200
	s_addc_u32 s19, s55, 0
	s_mov_b32 s3, 1
	s_mov_b64 s[22:23], 0
	v_mov_b32_e32 v1, 0
	s_branch .LBB0_74

; __device__ __forceinline__ unsigned xb_ld(unsigned* p)              { return __hip_atomic_load(p, __ATOMIC_RELAXED, __HIP_MEMORY_SCOPE_AGENT); }
; #define XB_SPIN(cond, bar) do { unsigned _sp = 0; while (cond) { __builtin_amdgcn_s_sleep(1); \
;     if ((++_sp & 255u) == 0u) { if (xb_ld(&(bar)[XB_TMO])) break; if (_sp > XB_SPIN_CAP) { atomicAdd(&(bar)[XB_TMO], 1u); break; } } } } while (0)
; __device__ __forceinline__ void xcd_barrier(const XcdBarrier& b) {
;     ...
;             XB_SPIN(xb_ld(&bar[XB_XGEN(b.x)]) == gen, bar);
;             __builtin_amdgcn_fence(__ATOMIC_ACQUIRE, "agent");
;             asm volatile("s_waitcnt vmcnt(0)" ::: "memory");
.LBB0_83:
	s_or_b64 exec, exec, s[16:17]
	s_waitcnt vmcnt(0)
	s_waitcnt vmcnt(0)

; __device__ __forceinline__ unsigned xb_ld(unsigned* p)              { return __hip_atomic_load(p, __ATOMIC_RELAXED, __HIP_MEMORY_SCOPE_AGENT); }
; __device__ __forceinline__ unsigned xb_add(unsigned* p, unsigned v) { return __hip_atomic_fetch_add(p, v, __ATOMIC_RELAXED, __HIP_MEMORY_SCOPE_AGENT); }
; #define XB_SPIN(cond, bar) do { unsigned _sp = 0; while (cond) { __builtin_amdgcn_s_sleep(1); \
;     if ((++_sp & 255u) == 0u) { if (xb_ld(&(bar)[XB_TMO])) break; if (_sp > XB_SPIN_CAP) { atomicAdd(&(bar)[XB_TMO], 1u); break; } } } } while (0)
; __device__ __forceinline__ void xcd_barrier(const XcdBarrier& b) {
;     ...
;             const unsigned og = xb_add(&bar[XB_TOP], 1u);
;             const unsigned tg = og / nx;
;             if (og + 1u == (tg + 1u) * nx) xb_add(&bar[XB_TOPGEN], 1u);
;             else XB_SPIN(xb_ld(&bar[XB_TOPGEN]) == tg, bar);
;             __builtin_amdgcn_fence(__ATOMIC_ACQUIRE, "agent");
;             xb_add(&bar[XB_XGEN(b.x)], 1u);
;             asm volatile("s_waitcnt vmcnt(0)" ::: "memory");
.LBB0_101:
	s_or_b64 exec, exec, s[14:15]
	v_mov_b32_e32 v1, 0x2000
	v_mov_b32_e32 v2, 1
	s_waitcnt vmcnt(0)
	global_atomic_add v1, v2, s[6:7] offset:1024
	s_waitcnt vmcnt(0)

; __device__ __forceinline__ unsigned xb_ld(unsigned* p)              { return __hip_atomic_load(p, __ATOMIC_RELAXED, __HIP_MEMORY_SCOPE_AGENT); }
; __device__ __forceinline__ unsigned xb_add(unsigned* p, unsigned v) { return __hip_atomic_fetch_add(p, v, __ATOMIC_RELAXED, __HIP_MEMORY_SCOPE_AGENT); }
; #define XB_SPIN(cond, bar) do { unsigned _sp = 0; while (cond) { __builtin_amdgcn_s_sleep(1); \
;     if ((++_sp & 255u) == 0u) { if (xb_ld(&(bar)[XB_TMO])) break; if (_sp > XB_SPIN_CAP) { atomicAdd(&(bar)[XB_TMO], 1u); break; } } } } while (0)
; __device__ __forceinline__ void xcd_barrier(const XcdBarrier& b) {
;     ...
;     if (threadIdx.x == 0) {
;         unsigned* bar = b.bar;
;         __builtin_amdgcn_s_waitcnt(0);
;         unsigned nloc = b.st[0], nx = b.st[1];
;         if (nloc == 0u) { xcd_barrier_complete(bar, b.x, nloc, nx); b.st[0] = nloc; b.st[1] = nx; }
;         const unsigned old = xb_add(&bar[XB_XSUB(b.x)], 1u);
;         const unsigned gen = old / nloc;
;         if (old + 1u == (gen + 1u) * nloc) {
;             __builtin_amdgcn_fence(__ATOMIC_RELEASE, "agent");
;             asm volatile("s_waitcnt vmcnt(0)" ::: "memory");
;             const unsigned og = xb_add(&bar[XB_TOP], 1u);
;             const unsigned tg = og / nx;
;             if (og + 1u == (tg + 1u) * nx) xb_add(&bar[XB_TOPGEN], 1u);
;             else XB_SPIN(xb_ld(&bar[XB_TOPGEN]) == tg, bar);
;             __builtin_amdgcn_fence(__ATOMIC_ACQUIRE, "agent");
;             xb_add(&bar[XB_XGEN(b.x)], 1u);
;             asm volatile("s_waitcnt vmcnt(0)" ::: "memory");
;         } else {
;             XB_SPIN(xb_ld(&bar[XB_XGEN(b.x)]) == gen, bar);
.LBB0_338:
	s_lshl_b32 s3, s33, 8
	s_add_u32 s4, s38, s3
	s_addc_u32 s5, s39, 0
	v_mov_b32_e32 v2, 0x1000
	v_mov_b32_e32 v4, 1
	buffer_inv sc1
	global_atomic_add v4, v2, v4, s[4:5] offset:1024 sc0
	v_cvt_f32_u32_e32 v2, v3
	v_sub_u32_e32 v5, 0, v3
	v_rcp_iflag_f32_e32 v2, v2
	s_nop 0
	v_mul_f32_e32 v2, 0x4f7ffffe, v2
	v_cvt_u32_f32_e32 v2, v2
	v_mul_lo_u32 v5, v5, v2
	v_mul_hi_u32 v5, v2, v5
	v_add_u32_e32 v2, v2, v5
	s_waitcnt vmcnt(0)
	v_mul_hi_u32 v2, v4, v2
	v_mul_lo_u32 v5, v2, v3
	v_sub_u32_e32 v5, v4, v5
	v_add_u32_e32 v6, 1, v2
	v_cmp_ge_u32_e32 vcc, v5, v3
	v_add_u32_e32 v4, 1, v4
	s_nop 0
	v_cndmask_b32_e32 v2, v2, v6, vcc
	v_sub_u32_e32 v6, v5, v3
	v_cndmask_b32_e32 v5, v5, v6, vcc
	v_add_u32_e32 v6, 1, v2
	v_cmp_ge_u32_e32 vcc, v5, v3
	s_nop 1
	v_cndmask_b32_e32 v2, v2, v6, vcc
	v_mul_lo_u32 v5, v3, v2
	v_add_u32_e32 v3, v5, v3
	v_cmp_ne_u32_e32 vcc, v4, v3
	s_and_saveexec_b64 s[14:15], vcc
	s_xor_b64 s[14:15], exec, s[14:15]
	s_cbranch_execz .LBB0_352
	s_waitcnt lgkmcnt(0)
	v_mov_b32_e32 v1, 0x2000
	global_load_dword v1, v1, s[4:5] offset:1024 sc1
	s_add_u32 s20, s4, 0x2400
	s_addc_u32 s21, s5, 0
	s_waitcnt vmcnt(0)
	v_cmp_eq_u32_e32 vcc, v1, v2
	s_and_saveexec_b64 s[16:17], vcc
	s_cbranch_execz .LBB0_351
	s_add_u32 s18, s54, 0x4200
	s_addc_u32 s19, s55, 0
	s_mov_b32 s3, 1
	s_mov_b64 s[22:23], 0
	v_mov_b32_e32 v1, 0
	s_branch .LBB0_342

; __device__ __forceinline__ unsigned xb_ld(unsigned* p)              { return __hip_atomic_load(p, __ATOMIC_RELAXED, __HIP_MEMORY_SCOPE_AGENT); }
; __device__ __forceinline__ unsigned xb_add(unsigned* p, unsigned v) { return __hip_atomic_fetch_add(p, v, __ATOMIC_RELAXED, __HIP_MEMORY_SCOPE_AGENT); }
; #define XB_SPIN(cond, bar) do { unsigned _sp = 0; while (cond) { __builtin_amdgcn_s_sleep(1); \
;     if ((++_sp & 255u) == 0u) { if (xb_ld(&(bar)[XB_TMO])) break; if (_sp > XB_SPIN_CAP) { atomicAdd(&(bar)[XB_TMO], 1u); break; } } } } while (0)
; __device__ __forceinline__ void xcd_barrier(const XcdBarrier& b) {
;     ...
;             const unsigned og = xb_add(&bar[XB_TOP], 1u);
;             const unsigned tg = og / nx;
;             if (og + 1u == (tg + 1u) * nx) xb_add(&bar[XB_TOPGEN], 1u);
;             else XB_SPIN(xb_ld(&bar[XB_TOPGEN]) == tg, bar);
;             __builtin_amdgcn_fence(__ATOMIC_ACQUIRE, "agent");
;             xb_add(&bar[XB_XGEN(b.x)], 1u);
;             asm volatile("s_waitcnt vmcnt(0)" ::: "memory");
.LBB0_369:
	s_or_b64 exec, exec, s[14:15]
	v_mov_b32_e32 v1, 0x2000
	v_mov_b32_e32 v2, 1
	s_waitcnt vmcnt(0)
	global_atomic_add v1, v2, s[4:5] offset:1024
	s_waitcnt vmcnt(0)

; __device__ __forceinline__ unsigned xb_ld(unsigned* p)              { return __hip_atomic_load(p, __ATOMIC_RELAXED, __HIP_MEMORY_SCOPE_AGENT); }
; __device__ __forceinline__ unsigned xb_add(unsigned* p, unsigned v) { return __hip_atomic_fetch_add(p, v, __ATOMIC_RELAXED, __HIP_MEMORY_SCOPE_AGENT); }
; #define XB_SPIN(cond, bar) do { unsigned _sp = 0; while (cond) { __builtin_amdgcn_s_sleep(1); \
;     if ((++_sp & 255u) == 0u) { if (xb_ld(&(bar)[XB_TMO])) break; if (_sp > XB_SPIN_CAP) { atomicAdd(&(bar)[XB_TMO], 1u); break; } } } } while (0)
; __device__ __forceinline__ void xcd_barrier(const XcdBarrier& b) {
;     ...
;     if (threadIdx.x == 0) {
;         unsigned* bar = b.bar;
;         __builtin_amdgcn_s_waitcnt(0);
;         unsigned nloc = b.st[0], nx = b.st[1];
;         if (nloc == 0u) { xcd_barrier_complete(bar, b.x, nloc, nx); b.st[0] = nloc; b.st[1] = nx; }
;         const unsigned old = xb_add(&bar[XB_XSUB(b.x)], 1u);
;         const unsigned gen = old / nloc;
;         if (old + 1u == (gen + 1u) * nloc) {
;             __builtin_amdgcn_fence(__ATOMIC_RELEASE, "agent");
;             asm volatile("s_waitcnt vmcnt(0)" ::: "memory");
;             const unsigned og = xb_add(&bar[XB_TOP], 1u);
;             const unsigned tg = og / nx;
;             if (og + 1u == (tg + 1u) * nx) xb_add(&bar[XB_TOPGEN], 1u);
;             else XB_SPIN(xb_ld(&bar[XB_TOPGEN]) == tg, bar);
;             __builtin_amdgcn_fence(__ATOMIC_ACQUIRE, "agent");
;             xb_add(&bar[XB_XGEN(b.x)], 1u);
;             asm volatile("s_waitcnt vmcnt(0)" ::: "memory");
;         } else {
;             XB_SPIN(xb_ld(&bar[XB_XGEN(b.x)]) == gen, bar);
.LBB0_440:
	s_lshl_b32 s3, s33, 8
	s_add_u32 s4, s38, s3
	s_addc_u32 s5, s39, 0
	v_mov_b32_e32 v2, 0x1000
	v_mov_b32_e32 v4, 1
	buffer_inv sc1
	global_atomic_add v4, v2, v4, s[4:5] offset:1024 sc0
	v_cvt_f32_u32_e32 v2, v3
	v_sub_u32_e32 v5, 0, v3
	v_rcp_iflag_f32_e32 v2, v2
	s_nop 0
	v_mul_f32_e32 v2, 0x4f7ffffe, v2
	v_cvt_u32_f32_e32 v2, v2
	v_mul_lo_u32 v5, v5, v2
	v_mul_hi_u32 v5, v2, v5
	v_add_u32_e32 v2, v2, v5
	s_waitcnt vmcnt(0)
	v_mul_hi_u32 v2, v4, v2
	v_mul_lo_u32 v5, v2, v3
	v_sub_u32_e32 v5, v4, v5
	v_add_u32_e32 v6, 1, v2
	v_cmp_ge_u32_e32 vcc, v5, v3
	v_add_u32_e32 v4, 1, v4
	s_nop 0
	v_cndmask_b32_e32 v2, v2, v6, vcc
	v_sub_u32_e32 v6, v5, v3
	v_cndmask_b32_e32 v5, v5, v6, vcc
	v_add_u32_e32 v6, 1, v2
	v_cmp_ge_u32_e32 vcc, v5, v3
	s_nop 1
	v_cndmask_b32_e32 v2, v2, v6, vcc
	v_mul_lo_u32 v5, v3, v2
	v_add_u32_e32 v3, v5, v3
	v_cmp_ne_u32_e32 vcc, v4, v3
	s_and_saveexec_b64 s[6:7], vcc
	s_xor_b64 s[6:7], exec, s[6:7]
	s_cbranch_execz .LBB0_454
	s_waitcnt lgkmcnt(0)
	v_mov_b32_e32 v1, 0x2000
	global_load_dword v1, v1, s[4:5] offset:1024 sc1
	s_add_u32 s18, s4, 0x2400
	s_addc_u32 s19, s5, 0
	s_waitcnt vmcnt(0)
	v_cmp_eq_u32_e32 vcc, v1, v2
	s_and_saveexec_b64 s[14:15], vcc
	s_cbranch_execz .LBB0_453
	s_add_u32 s16, s54, 0x4200
	s_addc_u32 s17, s55, 0
	s_mov_b32 s3, 1
	s_mov_b64 s[20:21], 0
	v_mov_b32_e32 v1, 0
	s_branch .LBB0_444

; __device__ __forceinline__ unsigned xb_ld(unsigned* p)              { return __hip_atomic_load(p, __ATOMIC_RELAXED, __HIP_MEMORY_SCOPE_AGENT); }
; #define XB_SPIN(cond, bar) do { unsigned _sp = 0; while (cond) { __builtin_amdgcn_s_sleep(1); \
;     if ((++_sp & 255u) == 0u) { if (xb_ld(&(bar)[XB_TMO])) break; if (_sp > XB_SPIN_CAP) { atomicAdd(&(bar)[XB_TMO], 1u); break; } } } } while (0)
; __device__ __forceinline__ void xcd_barrier(const XcdBarrier& b) {
;     ...
;             XB_SPIN(xb_ld(&bar[XB_XGEN(b.x)]) == gen, bar);
;             __builtin_amdgcn_fence(__ATOMIC_ACQUIRE, "agent");
;             asm volatile("s_waitcnt vmcnt(0)" ::: "memory");
.LBB0_453:
	s_or_b64 exec, exec, s[14:15]
	s_waitcnt vmcnt(0)
	s_waitcnt vmcnt(0)

; __device__ __forceinline__ unsigned xb_ld(unsigned* p)              { return __hip_atomic_load(p, __ATOMIC_RELAXED, __HIP_MEMORY_SCOPE_AGENT); }
; __device__ __forceinline__ unsigned xb_add(unsigned* p, unsigned v) { return __hip_atomic_fetch_add(p, v, __ATOMIC_RELAXED, __HIP_MEMORY_SCOPE_AGENT); }
; #define XB_SPIN(cond, bar) do { unsigned _sp = 0; while (cond) { __builtin_amdgcn_s_sleep(1); \
;     if ((++_sp & 255u) == 0u) { if (xb_ld(&(bar)[XB_TMO])) break; if (_sp > XB_SPIN_CAP) { atomicAdd(&(bar)[XB_TMO], 1u); break; } } } } while (0)
; __device__ __forceinline__ void xcd_barrier(const XcdBarrier& b) {
;     ...
;             const unsigned og = xb_add(&bar[XB_TOP], 1u);
;             const unsigned tg = og / nx;
;             if (og + 1u == (tg + 1u) * nx) xb_add(&bar[XB_TOPGEN], 1u);
;             else XB_SPIN(xb_ld(&bar[XB_TOPGEN]) == tg, bar);
;             __builtin_amdgcn_fence(__ATOMIC_ACQUIRE, "agent");
;             xb_add(&bar[XB_XGEN(b.x)], 1u);
;             asm volatile("s_waitcnt vmcnt(0)" ::: "memory");
.LBB0_471:
	s_or_b64 exec, exec, s[6:7]
	v_mov_b32_e32 v1, 0x2000
	v_mov_b32_e32 v2, 1
	s_waitcnt vmcnt(0)
	global_atomic_add v1, v2, s[4:5] offset:1024
	s_waitcnt vmcnt(0)

; __device__ __forceinline__ unsigned xb_add(unsigned* p, unsigned v) { return __hip_atomic_fetch_add(p, v, __ATOMIC_RELAXED, __HIP_MEMORY_SCOPE_AGENT); }
; __device__ __forceinline__ void xcd_barrier(const XcdBarrier& b) {
;     ...
;             __builtin_amdgcn_fence(__ATOMIC_ACQUIRE, "agent");
;             xb_add(&bar[XB_XGEN(b.x)], 1u);
;             asm volatile("s_waitcnt vmcnt(0)" ::: "memory");
.LBB0_474:
	s_or_b64 exec, exec, s[4:5]
	v_readlane_b32 s4, v245, 50
	v_readlane_b32 s5, v245, 51
	s_waitcnt vmcnt(0)
	s_nop 2
	global_atomic_add v3, v213, s[4:5]
	s_waitcnt vmcnt(0)

; __device__ __forceinline__ unsigned xb_ld(unsigned* p)              { return __hip_atomic_load(p, __ATOMIC_RELAXED, __HIP_MEMORY_SCOPE_AGENT); }
; __device__ __forceinline__ unsigned xb_add(unsigned* p, unsigned v) { return __hip_atomic_fetch_add(p, v, __ATOMIC_RELAXED, __HIP_MEMORY_SCOPE_AGENT); }
; #define XB_SPIN(cond, bar) do { unsigned _sp = 0; while (cond) { __builtin_amdgcn_s_sleep(1); \
;     if ((++_sp & 255u) == 0u) { if (xb_ld(&(bar)[XB_TMO])) break; if (_sp > XB_SPIN_CAP) { atomicAdd(&(bar)[XB_TMO], 1u); break; } } } } while (0)
; __device__ __forceinline__ void xcd_barrier(const XcdBarrier& b) {
;     ...
;     if (threadIdx.x == 0) {
;         unsigned* bar = b.bar;
;         __builtin_amdgcn_s_waitcnt(0);
;         unsigned nloc = b.st[0], nx = b.st[1];
;         if (nloc == 0u) { xcd_barrier_complete(bar, b.x, nloc, nx); b.st[0] = nloc; b.st[1] = nx; }
;         const unsigned old = xb_add(&bar[XB_XSUB(b.x)], 1u);
;         const unsigned gen = old / nloc;
;         if (old + 1u == (gen + 1u) * nloc) {
;             __builtin_amdgcn_fence(__ATOMIC_RELEASE, "agent");
;             asm volatile("s_waitcnt vmcnt(0)" ::: "memory");
;             const unsigned og = xb_add(&bar[XB_TOP], 1u);
;             const unsigned tg = og / nx;
;             if (og + 1u == (tg + 1u) * nx) xb_add(&bar[XB_TOPGEN], 1u);
;             else XB_SPIN(xb_ld(&bar[XB_TOPGEN]) == tg, bar);
;             __builtin_amdgcn_fence(__ATOMIC_ACQUIRE, "agent");
;             xb_add(&bar[XB_XGEN(b.x)], 1u);
;             asm volatile("s_waitcnt vmcnt(0)" ::: "memory");
;         } else {
;             XB_SPIN(xb_ld(&bar[XB_XGEN(b.x)]) == gen, bar);
.LBB0_553:
	v_readlane_b32 s4, v245, 48
	v_readlane_b32 s5, v245, 49
	v_cvt_f32_u32_e32 v2, v5
	v_sub_u32_e32 v7, 0, v5
	v_rcp_iflag_f32_e32 v2, v2
	s_nop 1
	buffer_inv sc1
	global_atomic_add v6, v3, v213, s[4:5] sc0
	v_mul_f32_e32 v2, 0x4f7ffffe, v2
	v_cvt_u32_f32_e32 v2, v2
	v_mul_lo_u32 v7, v7, v2
	v_mul_hi_u32 v7, v2, v7
	v_add_u32_e32 v2, v2, v7
	s_waitcnt vmcnt(0)
	v_mul_hi_u32 v2, v6, v2
	v_mul_lo_u32 v7, v2, v5
	v_sub_u32_e32 v7, v6, v7
	v_add_u32_e32 v8, 1, v2
	v_cmp_ge_u32_e32 vcc, v7, v5
	v_add_u32_e32 v6, 1, v6
	s_nop 0
	v_cndmask_b32_e32 v2, v2, v8, vcc
	v_sub_u32_e32 v8, v7, v5
	v_cndmask_b32_e32 v7, v7, v8, vcc
	v_add_u32_e32 v8, 1, v2
	v_cmp_ge_u32_e32 vcc, v7, v5
	s_nop 1
	v_cndmask_b32_e32 v2, v2, v8, vcc
	v_mul_lo_u32 v7, v5, v2
	v_add_u32_e32 v5, v7, v5
	v_cmp_ne_u32_e32 vcc, v6, v5
	s_and_saveexec_b64 s[4:5], vcc
	s_xor_b64 s[4:5], exec, s[4:5]
	s_cbranch_execz .LBB0_567
	v_readlane_b32 s6, v245, 50
	v_readlane_b32 s7, v245, 51
	s_waitcnt lgkmcnt(0)
	s_nop 3
	global_load_dword v4, v3, s[6:7] sc1
	s_waitcnt vmcnt(0)
	v_cmp_eq_u32_e32 vcc, v4, v2
	s_and_saveexec_b64 s[6:7], vcc
	s_cbranch_execz .LBB0_566
	s_mov_b32 s25, 1
	s_mov_b64 s[14:15], 0
	s_branch .LBB0_557

; __device__ __forceinline__ unsigned xb_ld(unsigned* p)              { return __hip_atomic_load(p, __ATOMIC_RELAXED, __HIP_MEMORY_SCOPE_AGENT); }
; #define XB_SPIN(cond, bar) do { unsigned _sp = 0; while (cond) { __builtin_amdgcn_s_sleep(1); \
;     if ((++_sp & 255u) == 0u) { if (xb_ld(&(bar)[XB_TMO])) break; if (_sp > XB_SPIN_CAP) { atomicAdd(&(bar)[XB_TMO], 1u); break; } } } } while (0)
; __device__ __forceinline__ void xcd_barrier(const XcdBarrier& b) {
;     ...
;             XB_SPIN(xb_ld(&bar[XB_XGEN(b.x)]) == gen, bar);
;             __builtin_amdgcn_fence(__ATOMIC_ACQUIRE, "agent");
;             asm volatile("s_waitcnt vmcnt(0)" ::: "memory");
.LBB0_566:
	s_or_b64 exec, exec, s[6:7]
	s_waitcnt vmcnt(0)
	s_waitcnt vmcnt(0)

; __device__ __forceinline__ unsigned xb_ld(unsigned* p)              { return __hip_atomic_load(p, __ATOMIC_RELAXED, __HIP_MEMORY_SCOPE_AGENT); }
; __device__ __forceinline__ unsigned xb_add(unsigned* p, unsigned v) { return __hip_atomic_fetch_add(p, v, __ATOMIC_RELAXED, __HIP_MEMORY_SCOPE_AGENT); }
; #define XB_SPIN(cond, bar) do { unsigned _sp = 0; while (cond) { __builtin_amdgcn_s_sleep(1); \
;     if ((++_sp & 255u) == 0u) { if (xb_ld(&(bar)[XB_TMO])) break; if (_sp > XB_SPIN_CAP) { atomicAdd(&(bar)[XB_TMO], 1u); break; } } } } while (0)
; __device__ __forceinline__ void xcd_barrier(const XcdBarrier& b) {
;     ...
;     if (threadIdx.x == 0) {
;         unsigned* bar = b.bar;
;         __builtin_amdgcn_s_waitcnt(0);
;         unsigned nloc = b.st[0], nx = b.st[1];
;         if (nloc == 0u) { xcd_barrier_complete(bar, b.x, nloc, nx); b.st[0] = nloc; b.st[1] = nx; }
;         const unsigned old = xb_add(&bar[XB_XSUB(b.x)], 1u);
;         const unsigned gen = old / nloc;
;         if (old + 1u == (gen + 1u) * nloc) {
;             __builtin_amdgcn_fence(__ATOMIC_RELEASE, "agent");
;             asm volatile("s_waitcnt vmcnt(0)" ::: "memory");
;             const unsigned og = xb_add(&bar[XB_TOP], 1u);
;             const unsigned tg = og / nx;
;             if (og + 1u == (tg + 1u) * nx) xb_add(&bar[XB_TOPGEN], 1u);
;             else XB_SPIN(xb_ld(&bar[XB_TOPGEN]) == tg, bar);
;             __builtin_amdgcn_fence(__ATOMIC_ACQUIRE, "agent");
;             xb_add(&bar[XB_XGEN(b.x)], 1u);
;             asm volatile("s_waitcnt vmcnt(0)" ::: "memory");
;         } else {
;             XB_SPIN(xb_ld(&bar[XB_XGEN(b.x)]) == gen, bar);
.LBB0_2328:
	v_readlane_b32 s4, v245, 48
	v_readlane_b32 s5, v245, 49
	v_cvt_f32_u32_e32 v2, v5
	v_sub_u32_e32 v7, 0, v5
	v_rcp_iflag_f32_e32 v2, v2
	s_nop 1
	buffer_inv sc1
	global_atomic_add v6, v3, v213, s[4:5] sc0
	v_mul_f32_e32 v2, 0x4f7ffffe, v2
	v_cvt_u32_f32_e32 v2, v2
	v_mul_lo_u32 v7, v7, v2
	v_mul_hi_u32 v7, v2, v7
	v_add_u32_e32 v2, v2, v7
	s_waitcnt vmcnt(0)
	v_mul_hi_u32 v2, v6, v2
	v_mul_lo_u32 v7, v2, v5
	v_sub_u32_e32 v7, v6, v7
	v_add_u32_e32 v8, 1, v2
	v_cmp_ge_u32_e32 vcc, v7, v5
	v_add_u32_e32 v6, 1, v6
	s_nop 0
	v_cndmask_b32_e32 v2, v2, v8, vcc
	v_sub_u32_e32 v8, v7, v5
	v_cndmask_b32_e32 v7, v7, v8, vcc
	v_add_u32_e32 v8, 1, v2
	v_cmp_ge_u32_e32 vcc, v7, v5
	s_nop 1
	v_cndmask_b32_e32 v2, v2, v8, vcc
	v_mul_lo_u32 v7, v5, v2
	v_add_u32_e32 v5, v7, v5
	v_cmp_ne_u32_e32 vcc, v6, v5
	s_and_saveexec_b64 s[4:5], vcc
	s_xor_b64 s[4:5], exec, s[4:5]
	s_cbranch_execz .LBB0_2342
	v_readlane_b32 s6, v245, 50
	v_readlane_b32 s7, v245, 51
	s_waitcnt lgkmcnt(0)
	s_nop 3
	global_load_dword v4, v3, s[6:7] sc1
	s_waitcnt vmcnt(0)
	v_cmp_eq_u32_e32 vcc, v4, v2
	s_and_saveexec_b64 s[6:7], vcc
	s_cbranch_execz .LBB0_2341
	s_mov_b32 s24, 1
	s_mov_b64 s[14:15], 0
	s_branch .LBB0_2332
